# m10b + final RMSNorm loop re-laid so every store instruction writes whole 128-byte lines (two 4-element groups per lane)
# speedup vs baseline: 1.0227x; 1.0011x over previous
; __device__ __forceinline__ float rstd_of(const unsigned long long* ssq, int row) { return rsqrtf((float)ssq[row] * (1.0f / (SSQ_SCALE * 1024.0f)) + EPS); }
; __global__ void __launch_bounds__(512, 2) mk_fwd(Args a) {
;     ...
;         const float* gf = a.in[22];
;         for (int orow0 = gw * 4; orow0 < NOUT_ROWS; orow0 += NGW * 4) {
;             u32x4 hv[4][2]; float rs[4];
; #pragma unroll
;             for (int i = 0; i < 4; ++i) { const int row = orow0 + i;
;                 rs[i] = rstd_of(SSQ3, row);
; #pragma unroll
;                 for (int j = 0; j < 2; ++j) hv[i][j] = *(const u32x4*)(H + (size_t)row * D + (j * 64 + lane) * 8); }
; #pragma unroll
;             for (int j = 0; j < 2; ++j) { const int col = (j * 64 + lane) * 8; const f32x4 g0 = *(const f32x4*)(gf + col), g1 = *(const f32x4*)(gf + col + 4);
.LBB0_712:
	s_cmp_lt_i32 s30, 9
	s_cselect_b64 s[2:3], -1, 0
	s_cmp_gt_i32 s31, 8
	v_readlane_b32 s8, v254, 0
	s_cselect_b64 s[4:5], -1, 0
	s_cmpk_lt_i32 s8, 0x6000
	s_cselect_b64 s[6:7], -1, 0
	s_and_b64 s[2:3], s[2:3], s[6:7]
	s_and_b64 s[2:3], s[2:3], s[4:5]
	s_and_b64 vcc, exec, s[2:3]
	s_cbranch_vccz .LBB0_715
	s_load_dwordx4 s[12:15], s[0:1], 0xb0
	s_lshl_b32 s6, s8, 2
	s_ashr_i32 s7, s6, 31
	v_lshlrev_b32_e32 v24, 4, v203
	v_mov_b32_e32 v25, 0
	s_ashr_i32 s45, s44, 31
	s_lshl_b64 s[0:1], s[6:7], 11
	v_and_b32_e32 v0, 63, v202
	s_waitcnt lgkmcnt(0)
	v_lshl_add_u64 v[26:27], s[12:13], 0, v[24:25]
	s_lshl_b64 s[8:9], s[6:7], 3
	s_lshl_b64 s[10:11], s[44:45], 3
	v_lshl_or_b32 v48, v0, 3, s0
	v_mov_b32_e32 v49, s1
	s_lshl_b64 s[12:13], s[44:45], 11
	s_lshl_b64 s[0:1], s[6:7], 12
	s_add_u32 s0, s14, s0
	v_lshlrev_b32_e32 v24, 4, v0
	s_addc_u32 s1, s15, s1
	v_lshl_add_u64 v[50:51], s[0:1], 0, v[24:25]
	s_lshl_b64 s[14:15], s[44:45], 12
	v_mov_b32_e32 v68, 0x358637bd
	s_mov_b32 s7, 0x800000
	s_add_u32 s16, s28, 0x3200000
	s_addc_u32 s17, s29, 0
	v_lshl_add_u64 v[48:49], s[16:17], 0, v[48:49]
	s_add_u32 s0, s28, s8
	s_addc_u32 s1, s29, s9
	s_add_u32 s0, s0, 0x400000
	s_addc_u32 s1, s1, 0
	global_load_dwordx4 v[88:91], v[26:27], off
	global_load_dwordx4 v[92:95], v[26:27], off offset:1024
	global_load_dwordx4 v[96:99], v[26:27], off offset:2048
	global_load_dwordx4 v[100:103], v[26:27], off offset:3072
	v_add_co_u32_e32 v52, vcc, 0x1000, v48
	s_nop 1
	v_addc_co_u32_e32 v53, vcc, 0, v49, vcc
	global_load_dwordx4 v[136:139], v25, s[0:1]
	global_load_dwordx4 v[140:143], v25, s[0:1] offset:16
	global_load_dwordx2 v[104:105], v[48:49], off
	global_load_dwordx2 v[106:107], v[48:49], off offset:512
	global_load_dwordx2 v[108:109], v[48:49], off offset:1024
	global_load_dwordx2 v[110:111], v[48:49], off offset:1536
	global_load_dwordx2 v[112:113], v[48:49], off offset:2048
	global_load_dwordx2 v[114:115], v[48:49], off offset:2560
	global_load_dwordx2 v[116:117], v[48:49], off offset:3072
	global_load_dwordx2 v[118:119], v[48:49], off offset:3584
	global_load_dwordx2 v[120:121], v[52:53], off
	global_load_dwordx2 v[122:123], v[52:53], off offset:512
	global_load_dwordx2 v[124:125], v[52:53], off offset:1024
	global_load_dwordx2 v[126:127], v[52:53], off offset:1536
	global_load_dwordx2 v[128:129], v[52:53], off offset:2048
	global_load_dwordx2 v[130:131], v[52:53], off offset:2560
	global_load_dwordx2 v[132:133], v[52:53], off offset:3072
	global_load_dwordx2 v[134:135], v[52:53], off offset:3584
	s_waitcnt vmcnt(0)
	s_branch .Lp8_entry

; __device__ __forceinline__ float bf_lo(unsigned u) { return __uint_as_float(u << 16); }
; __device__ __forceinline__ float bf_hi(unsigned u) { return __uint_as_float(u & 0xffff0000u); }
; __device__ __forceinline__ float rstd_of(const unsigned long long* ssq, int row) { return rsqrtf((float)ssq[row] * (1.0f / (SSQ_SCALE * 1024.0f)) + EPS); }
; __global__ void __launch_bounds__(512, 2) mk_fwd(Args a) {
;     ...
;         for (int orow0 = gw * 4; orow0 < NOUT_ROWS; orow0 += NGW * 4) {
;             u32x4 hv[4][2]; float rs[4];
; #pragma unroll
;             for (int i = 0; i < 4; ++i) { const int row = orow0 + i;
;                 rs[i] = rstd_of(SSQ3, row);
; #pragma unroll
;                 for (int j = 0; j < 2; ++j) hv[i][j] = *(const u32x4*)(H + (size_t)row * D + (j * 64 + lane) * 8); }
; #pragma unroll
;             for (int j = 0; j < 2; ++j) { const int col = (j * 64 + lane) * 8; const f32x4 g0 = *(const f32x4*)(gf + col), g1 = *(const f32x4*)(gf + col + 4);
; #pragma unroll
;                 for (int i = 0; i < 4; ++i) { const u32x4 h4 = hv[i][j]; const float r = rs[i];
;                     f32x4 o0, o1; o0.x = bf_lo(h4.x) * r * g0.x; o0.y = bf_hi(h4.x) * r * g0.y; o0.z = bf_lo(h4.y) * r * g0.z; o0.w = bf_hi(h4.y) * r * g0.w;
;                     o1.x = bf_lo(h4.z) * r * g1.x; o1.y = bf_hi(h4.z) * r * g1.y; o1.z = bf_lo(h4.w) * r * g1.z; o1.w = bf_hi(h4.w) * r * g1.w;
;                     float* op = a.out + (size_t)(orow0 + i) * D + col; *(f32x4*)op = o0; *(f32x4*)(op + 4) = o1; } }
.Lp8_entry:
	v_mov_b64_e32 v[144:145], v[104:105]
	v_mov_b64_e32 v[146:147], v[106:107]
	v_mov_b64_e32 v[148:149], v[108:109]
	v_mov_b64_e32 v[150:151], v[110:111]
	v_mov_b64_e32 v[152:153], v[112:113]
	v_mov_b64_e32 v[154:155], v[114:115]
	v_mov_b64_e32 v[156:157], v[116:117]
	v_mov_b64_e32 v[158:159], v[118:119]
	v_mov_b64_e32 v[160:161], v[120:121]
	v_mov_b64_e32 v[162:163], v[122:123]
	v_mov_b64_e32 v[164:165], v[124:125]
	v_mov_b64_e32 v[166:167], v[126:127]
	v_mov_b64_e32 v[168:169], v[128:129]
	v_mov_b64_e32 v[170:171], v[130:131]
	v_mov_b64_e32 v[172:173], v[132:133]
	v_mov_b64_e32 v[174:175], v[134:135]
	v_mov_b64_e32 v[176:177], v[136:137]
	v_mov_b64_e32 v[178:179], v[138:139]
	v_mov_b64_e32 v[180:181], v[140:141]
	v_mov_b64_e32 v[182:183], v[142:143]
	s_add_i32 s6, s6, s44
	s_add_u32 s0, s0, s10
	s_addc_u32 s1, s1, s11
	v_lshl_add_u64 v[48:49], v[48:49], 0, s[12:13]
	s_cmp_lt_i32 s6, 0x18000
	s_cbranch_scc0 .Lp8_noload
	v_add_co_u32_e32 v52, vcc, 0x1000, v48
	s_nop 1
	v_addc_co_u32_e32 v53, vcc, 0, v49, vcc
	global_load_dwordx4 v[136:139], v25, s[0:1]
	global_load_dwordx4 v[140:143], v25, s[0:1] offset:16
	global_load_dwordx2 v[104:105], v[48:49], off
	global_load_dwordx2 v[106:107], v[48:49], off offset:512
	global_load_dwordx2 v[108:109], v[48:49], off offset:1024
	global_load_dwordx2 v[110:111], v[48:49], off offset:1536
	global_load_dwordx2 v[112:113], v[48:49], off offset:2048
	global_load_dwordx2 v[114:115], v[48:49], off offset:2560
	global_load_dwordx2 v[116:117], v[48:49], off offset:3072
	global_load_dwordx2 v[118:119], v[48:49], off offset:3584
	global_load_dwordx2 v[120:121], v[52:53], off
	global_load_dwordx2 v[122:123], v[52:53], off offset:512
	global_load_dwordx2 v[124:125], v[52:53], off offset:1024
	global_load_dwordx2 v[126:127], v[52:53], off offset:1536
	global_load_dwordx2 v[128:129], v[52:53], off offset:2048
	global_load_dwordx2 v[130:131], v[52:53], off offset:2560
	global_load_dwordx2 v[132:133], v[52:53], off offset:3072
	global_load_dwordx2 v[134:135], v[52:53], off offset:3584
.Lp8_noload:
	v_add_co_u32_e32 v54, vcc, 0x1000, v50
	s_nop 1
	v_addc_co_u32_e32 v55, vcc, 0, v51, vcc
	v_add_co_u32_e32 v56, vcc, 0x2000, v50
	s_nop 1
	v_addc_co_u32_e32 v57, vcc, 0, v51, vcc
	v_add_co_u32_e32 v58, vcc, 0x3000, v50
	s_nop 1
	v_addc_co_u32_e32 v59, vcc, 0, v51, vcc
	v_ffbh_u32_e32 v0, v177
	v_ffbh_u32_e32 v4, v179
	v_min_u32_e32 v2, 32, v0
	v_min_u32_e32 v6, 32, v4
	v_lshlrev_b64 v[0:1], v2, v[176:177]
	v_lshlrev_b64 v[4:5], v6, v[178:179]
	v_min_u32_e32 v0, 1, v0
	v_min_u32_e32 v4, 1, v4
	v_or_b32_e32 v0, v1, v0
	v_or_b32_e32 v4, v5, v4
	v_cvt_f32_u32_e32 v0, v0
	v_cvt_f32_u32_e32 v4, v4
	v_sub_u32_e32 v1, 32, v2
	v_sub_u32_e32 v5, 32, v6
	v_ldexp_f32 v0, v0, v1
	v_ldexp_f32 v4, v4, v5
	v_fmamk_f32 v0, v0, 0x30800000, v68
	v_fmamk_f32 v4, v4, 0x30800000, v68
	v_mul_f32_e32 v1, 0x4b800000, v0
	v_mul_f32_e32 v5, 0x4b800000, v4
	v_cmp_gt_f32_e32 vcc, s7, v0
	v_cmp_gt_f32_e64 s[2:3], s7, v4
	s_nop 0
	v_cndmask_b32_e32 v0, v0, v1, vcc
	v_cndmask_b32_e64 v4, v4, v5, s[2:3]
	v_rsq_f32_e32 v0, v0
	v_rsq_f32_e32 v4, v4
	v_mul_f32_e32 v1, 0x45800000, v0
	v_mul_f32_e32 v5, 0x45800000, v4
	v_cndmask_b32_e32 v60, v0, v1, vcc
	v_cndmask_b32_e64 v62, v4, v5, s[2:3]
	v_ffbh_u32_e32 v0, v181
	v_ffbh_u32_e32 v4, v183
	v_min_u32_e32 v2, 32, v0
	v_min_u32_e32 v6, 32, v4
	v_lshlrev_b64 v[0:1], v2, v[180:181]
	v_lshlrev_b64 v[4:5], v6, v[182:183]
	v_min_u32_e32 v0, 1, v0
	v_min_u32_e32 v4, 1, v4
	v_or_b32_e32 v0, v1, v0
	v_or_b32_e32 v4, v5, v4
	v_cvt_f32_u32_e32 v0, v0
	v_cvt_f32_u32_e32 v4, v4
	v_sub_u32_e32 v1, 32, v2
	v_sub_u32_e32 v5, 32, v6
	v_ldexp_f32 v0, v0, v1
	v_ldexp_f32 v4, v4, v5
	v_fmamk_f32 v0, v0, 0x30800000, v68
	v_fmamk_f32 v4, v4, 0x30800000, v68
	v_mul_f32_e32 v1, 0x4b800000, v0
	v_mul_f32_e32 v5, 0x4b800000, v4
	v_cmp_gt_f32_e32 vcc, s7, v0
	v_cmp_gt_f32_e64 s[2:3], s7, v4
	s_nop 0
	v_cndmask_b32_e32 v0, v0, v1, vcc
	v_cndmask_b32_e64 v4, v4, v5, s[2:3]
	v_rsq_f32_e32 v0, v0
	v_rsq_f32_e32 v4, v4
	v_mul_f32_e32 v1, 0x45800000, v0
	v_mul_f32_e32 v5, 0x45800000, v4
	v_cndmask_b32_e32 v64, v0, v1, vcc
	v_cndmask_b32_e64 v66, v4, v5, s[2:3]
	v_lshlrev_b32_e32 v16, 16, v144
	v_and_b32_e32 v17, 0xffff0000, v144
	v_lshlrev_b32_e32 v18, 16, v145
	v_and_b32_e32 v19, 0xffff0000, v145
	v_lshlrev_b32_e32 v20, 16, v146
	v_and_b32_e32 v21, 0xffff0000, v146
	v_lshlrev_b32_e32 v22, 16, v147
	v_and_b32_e32 v23, 0xffff0000, v147
	v_pk_mul_f32 v[16:17], v[60:61], v[16:17] op_sel_hi:[0,1]
	v_pk_mul_f32 v[18:19], v[60:61], v[18:19] op_sel_hi:[0,1]
	v_pk_mul_f32 v[20:21], v[60:61], v[20:21] op_sel_hi:[0,1]
	v_pk_mul_f32 v[22:23], v[60:61], v[22:23] op_sel_hi:[0,1]
	v_pk_mul_f32 v[32:33], v[88:89], v[16:17]
	v_pk_mul_f32 v[34:35], v[90:91], v[18:19]
	v_pk_mul_f32 v[36:37], v[92:93], v[20:21]
	v_pk_mul_f32 v[38:39], v[94:95], v[22:23]
	global_store_dwordx4 v[50:51], v[32:35], off
	global_store_dwordx4 v[50:51], v[36:39], off offset:1024
	v_lshlrev_b32_e32 v16, 16, v148
	v_and_b32_e32 v17, 0xffff0000, v148
	v_lshlrev_b32_e32 v18, 16, v149
	v_and_b32_e32 v19, 0xffff0000, v149
	v_lshlrev_b32_e32 v20, 16, v150
	v_and_b32_e32 v21, 0xffff0000, v150
	v_lshlrev_b32_e32 v22, 16, v151
	v_and_b32_e32 v23, 0xffff0000, v151
	v_pk_mul_f32 v[16:17], v[60:61], v[16:17] op_sel_hi:[0,1]
	v_pk_mul_f32 v[18:19], v[60:61], v[18:19] op_sel_hi:[0,1]
; __device__ __forceinline__ float bf_lo(unsigned u) { return __uint_as_float(u << 16); }
; __device__ __forceinline__ float bf_hi(unsigned u) { return __uint_as_float(u & 0xffff0000u); }
; __global__ void __launch_bounds__(512, 2) mk_fwd(Args a) {
;     ...
;             for (int j = 0; j < 2; ++j) { const int col = (j * 64 + lane) * 8; const f32x4 g0 = *(const f32x4*)(gf + col), g1 = *(const f32x4*)(gf + col + 4);
; #pragma unroll
;                 for (int i = 0; i < 4; ++i) { const u32x4 h4 = hv[i][j]; const float r = rs[i];
;                     f32x4 o0, o1; o0.x = bf_lo(h4.x) * r * g0.x; o0.y = bf_hi(h4.x) * r * g0.y; o0.z = bf_lo(h4.y) * r * g0.z; o0.w = bf_hi(h4.y) * r * g0.w;
;                     o1.x = bf_lo(h4.z) * r * g1.x; o1.y = bf_hi(h4.z) * r * g1.y; o1.z = bf_lo(h4.w) * r * g1.z; o1.w = bf_hi(h4.w) * r * g1.w;
;                     float* op = a.out + (size_t)(orow0 + i) * D + col; *(f32x4*)op = o0; *(f32x4*)(op + 4) = o1; } }
;         }
	v_pk_mul_f32 v[20:21], v[60:61], v[20:21] op_sel_hi:[0,1]
	v_pk_mul_f32 v[22:23], v[60:61], v[22:23] op_sel_hi:[0,1]
	v_pk_mul_f32 v[40:41], v[96:97], v[16:17]
	v_pk_mul_f32 v[42:43], v[98:99], v[18:19]
	v_pk_mul_f32 v[44:45], v[100:101], v[20:21]
	v_pk_mul_f32 v[46:47], v[102:103], v[22:23]
	global_store_dwordx4 v[50:51], v[40:43], off offset:2048
	global_store_dwordx4 v[50:51], v[44:47], off offset:3072
	v_lshlrev_b32_e32 v16, 16, v152
	v_and_b32_e32 v17, 0xffff0000, v152
	v_lshlrev_b32_e32 v18, 16, v153
	v_and_b32_e32 v19, 0xffff0000, v153
	v_lshlrev_b32_e32 v20, 16, v154
	v_and_b32_e32 v21, 0xffff0000, v154
	v_lshlrev_b32_e32 v22, 16, v155
	v_and_b32_e32 v23, 0xffff0000, v155
	v_pk_mul_f32 v[16:17], v[62:63], v[16:17] op_sel_hi:[0,1]
	v_pk_mul_f32 v[18:19], v[62:63], v[18:19] op_sel_hi:[0,1]
	v_pk_mul_f32 v[20:21], v[62:63], v[20:21] op_sel_hi:[0,1]
	v_pk_mul_f32 v[22:23], v[62:63], v[22:23] op_sel_hi:[0,1]
	v_pk_mul_f32 v[32:33], v[88:89], v[16:17]
	v_pk_mul_f32 v[34:35], v[90:91], v[18:19]
	v_pk_mul_f32 v[36:37], v[92:93], v[20:21]
	v_pk_mul_f32 v[38:39], v[94:95], v[22:23]
	global_store_dwordx4 v[54:55], v[32:35], off
	global_store_dwordx4 v[54:55], v[36:39], off offset:1024
	v_lshlrev_b32_e32 v16, 16, v156
	v_and_b32_e32 v17, 0xffff0000, v156
	v_lshlrev_b32_e32 v18, 16, v157
	v_and_b32_e32 v19, 0xffff0000, v157
	v_lshlrev_b32_e32 v20, 16, v158
	v_and_b32_e32 v21, 0xffff0000, v158
	v_lshlrev_b32_e32 v22, 16, v159
	v_and_b32_e32 v23, 0xffff0000, v159
	v_pk_mul_f32 v[16:17], v[62:63], v[16:17] op_sel_hi:[0,1]
	v_pk_mul_f32 v[18:19], v[62:63], v[18:19] op_sel_hi:[0,1]
	v_pk_mul_f32 v[20:21], v[62:63], v[20:21] op_sel_hi:[0,1]
	v_pk_mul_f32 v[22:23], v[62:63], v[22:23] op_sel_hi:[0,1]
	v_pk_mul_f32 v[40:41], v[96:97], v[16:17]
	v_pk_mul_f32 v[42:43], v[98:99], v[18:19]
	v_pk_mul_f32 v[44:45], v[100:101], v[20:21]
	v_pk_mul_f32 v[46:47], v[102:103], v[22:23]
	global_store_dwordx4 v[54:55], v[40:43], off offset:2048
	global_store_dwordx4 v[54:55], v[44:47], off offset:3072
	v_lshlrev_b32_e32 v16, 16, v160
	v_and_b32_e32 v17, 0xffff0000, v160
	v_lshlrev_b32_e32 v18, 16, v161
	v_and_b32_e32 v19, 0xffff0000, v161
	v_lshlrev_b32_e32 v20, 16, v162
	v_and_b32_e32 v21, 0xffff0000, v162
	v_lshlrev_b32_e32 v22, 16, v163
	v_and_b32_e32 v23, 0xffff0000, v163
	v_pk_mul_f32 v[16:17], v[64:65], v[16:17] op_sel_hi:[0,1]
	v_pk_mul_f32 v[18:19], v[64:65], v[18:19] op_sel_hi:[0,1]
	v_pk_mul_f32 v[20:21], v[64:65], v[20:21] op_sel_hi:[0,1]
	v_pk_mul_f32 v[22:23], v[64:65], v[22:23] op_sel_hi:[0,1]
	v_pk_mul_f32 v[32:33], v[88:89], v[16:17]
	v_pk_mul_f32 v[34:35], v[90:91], v[18:19]
	v_pk_mul_f32 v[36:37], v[92:93], v[20:21]
	v_pk_mul_f32 v[38:39], v[94:95], v[22:23]
	global_store_dwordx4 v[56:57], v[32:35], off
	global_store_dwordx4 v[56:57], v[36:39], off offset:1024
	v_lshlrev_b32_e32 v16, 16, v164
	v_and_b32_e32 v17, 0xffff0000, v164
	v_lshlrev_b32_e32 v18, 16, v165
	v_and_b32_e32 v19, 0xffff0000, v165
	v_lshlrev_b32_e32 v20, 16, v166
	v_and_b32_e32 v21, 0xffff0000, v166
	v_lshlrev_b32_e32 v22, 16, v167
	v_and_b32_e32 v23, 0xffff0000, v167
	v_pk_mul_f32 v[16:17], v[64:65], v[16:17] op_sel_hi:[0,1]
	v_pk_mul_f32 v[18:19], v[64:65], v[18:19] op_sel_hi:[0,1]
	v_pk_mul_f32 v[20:21], v[64:65], v[20:21] op_sel_hi:[0,1]
	v_pk_mul_f32 v[22:23], v[64:65], v[22:23] op_sel_hi:[0,1]
	v_pk_mul_f32 v[40:41], v[96:97], v[16:17]
	v_pk_mul_f32 v[42:43], v[98:99], v[18:19]
	v_pk_mul_f32 v[44:45], v[100:101], v[20:21]
	v_pk_mul_f32 v[46:47], v[102:103], v[22:23]
	global_store_dwordx4 v[56:57], v[40:43], off offset:2048
	global_store_dwordx4 v[56:57], v[44:47], off offset:3072
	v_lshlrev_b32_e32 v16, 16, v168
	v_and_b32_e32 v17, 0xffff0000, v168
	v_lshlrev_b32_e32 v18, 16, v169
	v_and_b32_e32 v19, 0xffff0000, v169
	v_lshlrev_b32_e32 v20, 16, v170
	v_and_b32_e32 v21, 0xffff0000, v170
	v_lshlrev_b32_e32 v22, 16, v171
	v_and_b32_e32 v23, 0xffff0000, v171
	v_pk_mul_f32 v[16:17], v[66:67], v[16:17] op_sel_hi:[0,1]
	v_pk_mul_f32 v[18:19], v[66:67], v[18:19] op_sel_hi:[0,1]
	v_pk_mul_f32 v[20:21], v[66:67], v[20:21] op_sel_hi:[0,1]
	v_pk_mul_f32 v[22:23], v[66:67], v[22:23] op_sel_hi:[0,1]
	v_pk_mul_f32 v[32:33], v[88:89], v[16:17]
	v_pk_mul_f32 v[34:35], v[90:91], v[18:19]
	v_pk_mul_f32 v[36:37], v[92:93], v[20:21]
	v_pk_mul_f32 v[38:39], v[94:95], v[22:23]
	global_store_dwordx4 v[58:59], v[32:35], off
	global_store_dwordx4 v[58:59], v[36:39], off offset:1024
	v_lshlrev_b32_e32 v16, 16, v172
	v_and_b32_e32 v17, 0xffff0000, v172
	v_lshlrev_b32_e32 v18, 16, v173
	v_and_b32_e32 v19, 0xffff0000, v173
	v_lshlrev_b32_e32 v20, 16, v174
	v_and_b32_e32 v21, 0xffff0000, v174
	v_lshlrev_b32_e32 v22, 16, v175
	v_and_b32_e32 v23, 0xffff0000, v175
	v_pk_mul_f32 v[16:17], v[66:67], v[16:17] op_sel_hi:[0,1]
	v_pk_mul_f32 v[18:19], v[66:67], v[18:19] op_sel_hi:[0,1]
	v_pk_mul_f32 v[20:21], v[66:67], v[20:21] op_sel_hi:[0,1]
	v_pk_mul_f32 v[22:23], v[66:67], v[22:23] op_sel_hi:[0,1]
	v_pk_mul_f32 v[40:41], v[96:97], v[16:17]
	v_pk_mul_f32 v[42:43], v[98:99], v[18:19]
	v_pk_mul_f32 v[44:45], v[100:101], v[20:21]
	v_pk_mul_f32 v[46:47], v[102:103], v[22:23]
	global_store_dwordx4 v[58:59], v[40:43], off offset:2048
	global_store_dwordx4 v[58:59], v[44:47], off offset:3072
	v_lshl_add_u64 v[50:51], v[50:51], 0, s[14:15]
	s_cmp_lt_i32 s6, 0x18000
	s_cbranch_scc1 .Lp8_top
